# plus: four more residual-tile pieces per lane kept in VGPRs that no other phase uses (v224-v239) across the residual-GEMM epilogues; LRU staging batch edit dropped
# speedup vs baseline: 1.0191x; 1.0080x over previous
.LBB0_906:
	v_or_b32_e32 v132, 0x80, v242
	v_add_u32_e32 v0, v132, v118
	v_lshl_add_u64 v[120:121], v[0:1], 1, s[10:11]
	v_add_u32_e32 v130, 0x4000, v0
	v_mov_b32_e32 v131, v1
	v_add_u32_e32 v0, 0x8000, v0
	v_lshl_add_u64 v[130:131], v[130:131], 1, s[10:11]
	s_cmp_eq_u32 s98, 0
	s_cbranch_scc1 .Lxr_g1
	v_mov_b32_e32 v218, v232
	v_mov_b32_e32 v219, v233
	v_mov_b32_e32 v220, v234
	v_mov_b32_e32 v221, v235
	v_mov_b32_e32 v233, v231
	v_mov_b32_e32 v232, v230
	v_mov_b32_e32 v231, v229
	v_mov_b32_e32 v230, v228
	s_branch .Lxr_d1
.Lxr_g1:
	global_load_dwordx4 v[230:233], v[120:121], off
	global_load_dwordx4 v[218:221], v[130:131], off
.Lxr_d1:
	v_lshl_add_u64 v[120:121], v[0:1], 1, s[10:11]
	v_add_u32_e32 v0, v119, v132
	v_lshl_add_u64 v[118:119], v[0:1], 1, s[10:11]
	s_cmp_eq_u32 s98, 0
	s_cbranch_scc1 .Lxr_g2
	v_mov_b32_e32 v198, v236
	v_mov_b32_e32 v199, v237
	v_mov_b32_e32 v200, v238
	v_mov_b32_e32 v201, v239
	v_mov_b32_e32 v170, v224
	v_mov_b32_e32 v171, v225
	v_mov_b32_e32 v172, v226
	v_mov_b32_e32 v173, v227
	s_branch .Lxr_d2
.Lxr_g2:
	global_load_dwordx4 v[198:201], v[120:121], off
	global_load_dwordx4 v[170:173], v[118:119], off
.Lxr_d2:
	v_add_u32_e32 v118, 0x4000, v0
	v_mov_b32_e32 v119, v1
	v_add_u32_e32 v0, 0x8000, v0
	v_lshl_add_u64 v[118:119], v[118:119], 1, s[10:11]
	v_lshl_add_u64 v[120:121], v[0:1], 1, s[10:11]
	global_load_dwordx4 v[142:145], v[118:119], off
	s_nop 0
	global_load_dwordx4 v[118:121], v[120:121], off
	s_and_b64 vcc, exec, s[0:1]
	v_mov_b64_e32 v[130:131], s[68:69]
	s_cbranch_vccnz .LBB0_908
	s_add_i32 s4, s14, 0xffffe000
	s_lshr_b32 s4, s4, 10
	s_mulk_i32 s4, 0x1800
	s_addk_i32 s4, 0x1800
	v_mov_b32_e32 v0, s4
	s_movk_i32 s4, 0x1fff
	v_cmp_lt_i32_e32 vcc, s4, v249
	s_nop 1
	v_cndmask_b32_e32 v0, 0, v0, vcc
	v_mov_b64_e32 v[130:131], v[0:1]

.LBB0_991:
	v_lshlrev_b64 v[2:3], 1, v[0:1]
	v_cvt_pk_bf16_f32 v100, v52, v53
	v_cvt_pk_bf16_f32 v101, v54, v55
	v_cvt_pk_bf16_f32 v102, v56, v57
	v_cvt_pk_bf16_f32 v103, v58, v59
	v_lshl_add_u64 v[104:105], s[10:11], 0, v[2:3]
	v_mov_b32_e32 v228, v100
	v_mov_b32_e32 v229, v101
	v_mov_b32_e32 v230, v102
	v_mov_b32_e32 v231, v103
	v_lshl_add_u64 v[2:3], s[78:79], 0, v[2:3]
	s_nop 0
	v_pk_fma_f32 v[102:103], v[54:55], v[38:39], v[22:23]
	v_pk_fma_f32 v[100:101], v[52:53], v[36:37], v[20:21]
	v_pk_fma_f32 v[104:105], v[58:59], v[46:47], v[30:31]
	v_pk_fma_f32 v[106:107], v[56:57], v[44:45], v[28:29]
	v_cvt_pk_bf16_f32 v100, v100, v101
	v_cvt_pk_bf16_f32 v101, v102, v103
	v_cvt_pk_bf16_f32 v103, v104, v105
	s_nop 0
	v_cvt_pk_bf16_f32 v102, v106, v107
	global_store_dwordx4 v[2:3], v[100:103], off
	s_branch .LBB0_993

.LBB0_996:
	v_lshlrev_b64 v[2:3], 1, v[0:1]
	v_cvt_pk_bf16_f32 v92, v52, v53
	v_cvt_pk_bf16_f32 v93, v54, v55
	v_cvt_pk_bf16_f32 v94, v56, v57
	v_cvt_pk_bf16_f32 v95, v58, v59
	v_lshl_add_u64 v[96:97], s[10:11], 0, v[2:3]
	v_mov_b32_e32 v232, v92
	v_mov_b32_e32 v233, v93
	v_mov_b32_e32 v234, v94
	v_mov_b32_e32 v235, v95
	v_lshl_add_u64 v[2:3], s[78:79], 0, v[2:3]
	s_nop 0
	v_pk_fma_f32 v[94:95], v[54:55], v[42:43], v[26:27]
	v_pk_fma_f32 v[92:93], v[52:53], v[40:41], v[24:25]
	v_pk_fma_f32 v[96:97], v[58:59], v[50:51], v[34:35]
	v_pk_fma_f32 v[100:101], v[56:57], v[48:49], v[32:33]
	v_cvt_pk_bf16_f32 v92, v92, v93
	v_cvt_pk_bf16_f32 v93, v94, v95
	v_cvt_pk_bf16_f32 v95, v96, v97
	s_nop 0
	v_cvt_pk_bf16_f32 v94, v100, v101
	global_store_dwordx4 v[2:3], v[92:95], off
	s_branch .LBB0_998

.LBB0_1001:
	v_lshlrev_b64 v[2:3], 1, v[0:1]
	v_cvt_pk_bf16_f32 v84, v52, v53
	v_cvt_pk_bf16_f32 v85, v54, v55
	v_cvt_pk_bf16_f32 v86, v56, v57
	v_cvt_pk_bf16_f32 v87, v58, v59
	v_lshl_add_u64 v[88:89], s[10:11], 0, v[2:3]
	v_mov_b32_e32 v236, v84
	v_mov_b32_e32 v237, v85
	v_mov_b32_e32 v238, v86
	v_mov_b32_e32 v239, v87
	v_lshl_add_u64 v[2:3], s[78:79], 0, v[2:3]
	s_nop 0
	v_pk_fma_f32 v[86:87], v[54:55], v[38:39], v[22:23]
	v_pk_fma_f32 v[84:85], v[52:53], v[36:37], v[20:21]
	v_pk_fma_f32 v[88:89], v[58:59], v[46:47], v[30:31]
	v_pk_fma_f32 v[90:91], v[56:57], v[44:45], v[28:29]
	v_cvt_pk_bf16_f32 v84, v84, v85
	v_cvt_pk_bf16_f32 v85, v86, v87
	v_cvt_pk_bf16_f32 v87, v88, v89
	s_nop 0
	v_cvt_pk_bf16_f32 v86, v90, v91
	global_store_dwordx4 v[2:3], v[84:87], off
	s_branch .LBB0_1003

.LBB0_1006:
	v_lshlrev_b64 v[2:3], 1, v[0:1]
	v_cvt_pk_bf16_f32 v76, v52, v53
	v_cvt_pk_bf16_f32 v77, v54, v55
	v_cvt_pk_bf16_f32 v78, v56, v57
	v_cvt_pk_bf16_f32 v79, v58, v59
	v_lshl_add_u64 v[80:81], s[10:11], 0, v[2:3]
	v_mov_b32_e32 v224, v76
	v_mov_b32_e32 v225, v77
	v_mov_b32_e32 v226, v78
	v_mov_b32_e32 v227, v79
	v_lshl_add_u64 v[2:3], s[78:79], 0, v[2:3]
	s_nop 0
	v_pk_fma_f32 v[78:79], v[54:55], v[42:43], v[26:27]
	v_pk_fma_f32 v[76:77], v[52:53], v[40:41], v[24:25]
	v_pk_fma_f32 v[80:81], v[58:59], v[50:51], v[34:35]
	v_pk_fma_f32 v[82:83], v[56:57], v[48:49], v[32:33]
	v_cvt_pk_bf16_f32 v76, v76, v77
	v_cvt_pk_bf16_f32 v77, v78, v79
	v_cvt_pk_bf16_f32 v79, v80, v81
	s_nop 0
	v_cvt_pk_bf16_f32 v78, v82, v83
	global_store_dwordx4 v[2:3], v[76:79], off
	s_branch .LBB0_1008
